# SB non-diag loop: QK MFMAs issued before V ds_writes and next-tile loads (MFMA/VMEM interleave), vmcnt(2) guard for first-iteration K
# speedup vs baseline: 1.0082x; 1.0005x over previous
.LBB0_400:
	v_cmp_ge_f32_e32 vcc, 0x8000, v146
	s_cmp_eq_u64 vcc, exec
	s_mov_b64 s[34:35], -1
	s_cbranch_scc1 .LBB0_399
	s_cmp_eq_u32 s80, 2
	s_cbranch_scc1 .LBB0_403
	s_waitcnt vmcnt(2)
	v_mfma_f32_32x32x16_bf16 v[32:47], v[32:35], v[48:51], 0
	v_mfma_f32_32x32x16_bf16 v[32:47], v[96:99], v[52:55], v[32:47]
	v_mfma_f32_32x32x16_bf16 v[32:47], v[100:103], v[56:59], v[32:47]
	v_mfma_f32_32x32x16_bf16 v[32:47], v[104:107], v[60:63], v[32:47]
	s_waitcnt vmcnt(5)
	ds_write_b128 v161, v[64:67]
	s_waitcnt vmcnt(4)
	ds_write_b128 v161, v[68:71] offset:512
	s_waitcnt vmcnt(1)
	ds_write_b128 v161, v[72:75] offset:1024
	s_waitcnt vmcnt(0)
	ds_write_b128 v161, v[76:79] offset:1536
	global_load_dwordx4 v[108:111], v[138:139], off offset:-4096
	global_load_dwordx4 v[112:115], v[138:139], off offset:-4064
	global_load_dwordx4 v[64:67], v[136:137], off offset:-4096
	global_load_dwordx4 v[68:71], v[136:137], off offset:-3072
	global_load_dwordx4 v[116:119], v[138:139], off offset:-4032
	global_load_dwordx4 v[120:123], v[138:139], off offset:-4000
	global_load_dwordx4 v[72:75], v[136:137], off offset:-2048
	global_load_dwordx4 v[76:79], v[136:137], off offset:-1024
	v_lshl_add_u64 v[138:139], v[138:139], 0, s[0:1]
	v_lshl_add_u64 v[136:137], v[136:137], 0, s[0:1]
	s_branch .LBB0_404
.LBB0_403:
	v_mov_b64_e32 v[110:111], v[34:35]
	v_mov_b64_e32 v[114:115], v[98:99]
	v_mov_b64_e32 v[118:119], v[102:103]
	v_mov_b64_e32 v[122:123], v[106:107]
	v_mov_b64_e32 v[108:109], v[32:33]
	v_mov_b64_e32 v[112:113], v[96:97]
	v_mov_b64_e32 v[116:117], v[100:101]
	v_mov_b64_e32 v[120:121], v[104:105]
	s_waitcnt vmcnt(2)
	v_mfma_f32_32x32x16_bf16 v[32:47], v[32:35], v[48:51], 0
	v_mfma_f32_32x32x16_bf16 v[32:47], v[96:99], v[52:55], v[32:47]
	v_mfma_f32_32x32x16_bf16 v[32:47], v[100:103], v[56:59], v[32:47]
	v_mfma_f32_32x32x16_bf16 v[32:47], v[104:107], v[60:63], v[32:47]
	s_waitcnt vmcnt(5)
	ds_write_b128 v161, v[64:67]
	s_waitcnt vmcnt(4)
	ds_write_b128 v161, v[68:71] offset:512
	s_waitcnt vmcnt(1)
	ds_write_b128 v161, v[72:75] offset:1024
	s_waitcnt vmcnt(0)
	ds_write_b128 v161, v[76:79] offset:1536
.LBB0_404:
	s_add_i32 s80, s80, -1
	s_cmp_lt_u32 s80, 2
	s_cselect_b64 s[34:35], -1, 0
	s_nop 1
	v_mul_f32_e32 v33, 0xbfb8aa3b, v33
	v_mul_f32_e32 v34, 0xbfb8aa3b, v34
	v_exp_f32_e32 v33, v33
	v_exp_f32_e32 v34, v34
	v_mul_f32_e32 v41, 0xbfb8aa3b, v41
	v_exp_f32_e32 v41, v41
	v_add_f32_e32 v33, 1.0, v33
	v_add_f32_e32 v96, 1.0, v34
	v_mul_f32_e32 v42, 0xbfb8aa3b, v42
	v_rcp_f32_e32 v34, v33
	v_rcp_f32_e32 v33, v96
	v_exp_f32_e32 v96, v42
	v_add_f32_e32 v41, 1.0, v41
	v_mul_f32_e32 v42, 0xbfb8aa3b, v43
	v_mul_f32_e32 v45, 0xbfb8aa3b, v45
	v_mul_f32_e32 v46, 0xbfb8aa3b, v46
	v_mul_f32_e32 v40, 0xbfb8aa3b, v40
	v_exp_f32_e32 v43, v42
	v_rcp_f32_e32 v42, v41
	v_add_f32_e32 v41, 1.0, v96
	v_mul_f32_e32 v44, 0xbfb8aa3b, v44
	v_exp_f32_e32 v45, v45
	v_exp_f32_e32 v96, v46
	v_mul_f32_e32 v46, 0xbfb8aa3b, v47
	v_exp_f32_e32 v40, v40
	v_exp_f32_e32 v44, v44
	v_exp_f32_e32 v47, v46
	v_add_f32_e32 v45, 1.0, v45
	v_add_f32_e32 v40, 1.0, v40
	v_add_f32_e32 v43, 1.0, v43
	v_add_f32_e32 v44, 1.0, v44
	v_rcp_f32_e32 v46, v45
	v_add_f32_e32 v45, 1.0, v96
	v_add_f32_e32 v47, 1.0, v47
	v_rcp_f32_e32 v40, v40
	v_rcp_f32_e32 v41, v41
	v_rcp_f32_e32 v43, v43
	v_rcp_f32_e32 v44, v44
	v_rcp_f32_e32 v45, v45
	v_rcp_f32_e32 v47, v47
	v_mul_f32_e32 v36, 0xbfb8aa3b, v36
	v_mul_f32_e32 v37, 0xbfb8aa3b, v37
	v_mul_f32_e32 v38, 0xbfb8aa3b, v38
	v_mul_f32_e32 v39, 0xbfb8aa3b, v39
	v_exp_f32_e32 v36, v36
	v_exp_f32_e32 v37, v37
	v_exp_f32_e32 v38, v38
	v_exp_f32_e32 v39, v39
	v_pk_add_f32 v[98:99], v[40:41], 1.0 op_sel_hi:[1,0] neg_lo:[1,0] neg_hi:[1,0]
	v_pk_add_f32 v[100:101], v[42:43], 1.0 op_sel_hi:[1,0] neg_lo:[1,0] neg_hi:[1,0]
	v_pk_add_f32 v[102:103], v[44:45], 1.0 op_sel_hi:[1,0] neg_lo:[1,0] neg_hi:[1,0]
	v_pk_add_f32 v[104:105], v[46:47], 1.0 op_sel_hi:[1,0] neg_lo:[1,0] neg_hi:[1,0]
	v_pk_mul_f32 v[98:99], v[98:99], v[100:101]
	v_pk_mul_f32 v[102:103], v[102:103], v[104:105]
	v_mov_b32_e32 v107, v98
	v_mov_b32_e32 v106, v102
	v_mov_b32_e32 v98, v103
	v_add_f32_e32 v36, 1.0, v36
	v_add_f32_e32 v37, 1.0, v37
	v_add_f32_e32 v97, 1.0, v38
	v_add_f32_e32 v39, 1.0, v39
	v_pk_mul_f32 v[106:107], v[106:107], v[98:99]
	v_mul_f32_e32 v32, 0xbfb8aa3b, v32
	v_mul_f32_e32 v35, 0xbfb8aa3b, v35
	v_rcp_f32_e32 v36, v36
	v_rcp_f32_e32 v38, v37
	v_rcp_f32_e32 v37, v97
	v_rcp_f32_e32 v39, v39
	ds_bpermute_b32 v167, v159, v107
	ds_bpermute_b32 v166, v159, v106
	v_exp_f32_e32 v32, v32
	v_exp_f32_e32 v35, v35
	v_pk_add_f32 v[170:171], v[36:37], 1.0 op_sel_hi:[1,0] neg_lo:[1,0] neg_hi:[1,0]
	v_pk_add_f32 v[172:173], v[38:39], 1.0 op_sel_hi:[1,0] neg_lo:[1,0] neg_hi:[1,0]
	v_add_f32_e32 v32, 1.0, v32
	v_add_f32_e32 v35, 1.0, v35
	v_pk_mul_f32 v[170:171], v[170:171], v[172:173]
	s_waitcnt lgkmcnt(0)
	v_pk_mul_f32 v[106:107], v[106:107], v[166:167]
	v_rcp_f32_e32 v32, v32
	v_rcp_f32_e32 v35, v35
	v_mov_b32_e32 v174, v170
	v_mov_b32_e32 v175, v106
	v_mov_b32_e32 v176, v171
	v_mov_b32_e32 v177, v107
	v_pk_mul_f32 v[174:175], v[174:175], v[176:177]
	ds_bpermute_b32 v177, v159, v174
	v_pk_add_f32 v[96:97], v[32:33], 1.0 op_sel_hi:[1,0] neg_lo:[1,0] neg_hi:[1,0]
	v_pk_add_f32 v[168:169], v[34:35], 1.0 op_sel_hi:[1,0] neg_lo:[1,0] neg_hi:[1,0]
	v_mov_b32_e32 v179, v174
	v_pk_mul_f32 v[96:97], v[96:97], v[168:169]
	v_mov_b32_e32 v182, v168
	v_mov_b32_e32 v178, v96
	v_mov_b32_e32 v176, v97
	s_waitcnt lgkmcnt(0)
	v_pk_mul_f32 v[178:179], v[178:179], v[176:177]
	ds_bpermute_b32 v174, v159, v178
	v_mov_b32_e32 v180, v97
	v_cndmask_b32_e64 v102, 1.0, v166, s[40:41]
	v_mov_b32_e32 v147, v104
	s_waitcnt lgkmcnt(0)
	v_pk_mul_f32 v[178:179], v[178:179], v[174:175]
	s_nop 0
	v_mul_f32_e32 v181, v146, v179
	v_cndmask_b32_e64 v183, 1.0, v174, s[40:41]
	v_pk_mul_f32 v[180:181], v[182:183], v[180:181]
	s_nop 0
	v_mul_f32_e32 v96, v180, v181
	v_mul_f32_e32 v96, v32, v96
	v_mul_f32_e32 v32, v97, v181
	v_mul_f32_e32 v97, v34, v32
	v_mul_f32_e32 v32, v169, v181
	v_mul_f32_e32 v98, v33, v32
	v_mul_f32_e32 v107, v35, v181
	v_mul_f32_e32 v33, v146, v175
	v_cndmask_b32_e64 v35, 1.0, v177, s[40:41]
	v_mov_b32_e32 v34, v172
	v_mov_b32_e32 v32, v171
	v_pk_mul_f32 v[32:33], v[34:35], v[32:33]
	v_cndmask_b32_e64 v35, 1.0, v167, s[40:41]
	v_mul_f32_e32 v32, v32, v33
	v_mul_f32_e32 v36, v36, v32
	v_mul_f32_e32 v32, v171, v33
	v_mul_f32_e32 v38, v38, v32
	v_mul_f32_e32 v32, v173, v33
	v_mul_f32_e32 v37, v37, v32
	v_mul_f32_e32 v39, v39, v33
	v_mul_f32_e32 v33, v146, v106
	v_mov_b32_e32 v34, v100
	v_mov_b32_e32 v32, v99
	v_pk_mul_f32 v[32:33], v[34:35], v[32:33]
	s_nop 0
	v_mul_f32_e32 v32, v32, v33
	v_mul_f32_e32 v40, v40, v32
	v_mul_f32_e32 v32, v99, v33
	v_mul_f32_e32 v42, v42, v32
	v_mul_f32_e32 v32, v101, v33
	v_mul_f32_e32 v41, v41, v32
	v_mul_f32_e32 v43, v43, v33
	v_pk_mul_f32 v[32:33], v[146:147], v[102:103]
	s_nop 0
	v_mul_f32_e32 v33, v32, v33
	v_mul_f32_e32 v44, v44, v33
	v_mul_f32_e32 v33, v32, v103
	v_mul_f32_e32 v46, v46, v33
	v_mul_f32_e32 v33, v32, v105
	v_mul_f32_e32 v45, v45, v33
	v_mul_f32_e32 v47, v47, v32
	v_cvt_pk_bf16_f32 v32, v96, v97
	v_cvt_pk_bf16_f32 v33, v98, v107
	v_cvt_pk_bf16_f32 v34, v36, v38
	v_cvt_pk_bf16_f32 v35, v37, v39
	v_cvt_pk_bf16_f32 v36, v40, v42
	v_cvt_pk_bf16_f32 v37, v41, v43
	v_cvt_pk_bf16_f32 v38, v44, v46
	v_cvt_pk_bf16_f32 v39, v45, v47
	ds_read_b64_tr_b16 v[40:41], v162
	ds_read_b64_tr_b16 v[42:43], v162 offset:512
	ds_read_b64_tr_b16 v[44:45], v162 offset:2048
	ds_read_b64_tr_b16 v[46:47], v162 offset:2560
	ds_read_b64_tr_b16 v[96:97], v162 offset:1024
	ds_read_b64_tr_b16 v[98:99], v162 offset:1536
	ds_read_b64_tr_b16 v[100:101], v162 offset:3072
	ds_read_b64_tr_b16 v[102:103], v162 offset:3584
	s_waitcnt lgkmcnt(6)
	v_mfma_f32_32x32x16_bf16 v[0:15], v[32:35], v[40:43], v[0:15]
	s_waitcnt lgkmcnt(4)
	v_mfma_f32_32x32x16_bf16 v[16:31], v[32:35], v[44:47], v[16:31]
	s_waitcnt lgkmcnt(2)
	v_mfma_f32_32x32x16_bf16 v[0:15], v[36:39], v[96:99], v[0:15]
	s_waitcnt lgkmcnt(0)
	v_mfma_f32_32x32x16_bf16 v[16:31], v[36:39], v[100:103], v[16:31]
	s_waitcnt vmcnt(2)
	v_mov_b64_e32 v[104:105], v[120:121]
	v_mov_b64_e32 v[100:101], v[116:117]
	v_mov_b64_e32 v[96:97], v[112:113]
	v_mul_f32_e32 v32, v178, v179
	v_mul_f32_e32 v146, v146, v32
	v_mov_b64_e32 v[32:33], v[108:109]
	v_mov_b64_e32 v[106:107], v[122:123]
	v_mov_b64_e32 v[102:103], v[118:119]
	v_mov_b64_e32 v[98:99], v[114:115]
	v_mov_b64_e32 v[34:35], v[110:111]
	s_and_b64 vcc, exec, s[34:35]
	s_cbranch_vccz .LBB0_400
